# v102 + split cache policy on SwiGLU activation stores: nt only for the row group written in the first half of FFN-in; the late-written half stays cacheable so the reversed FFN-out order finds it in th
# speedup vs baseline: 1.0182x; 1.0109x over previous
.LBB0_183:
	v_mul_f32_e32 v159, 0xbfb8aa3b, v124
	v_exp_f32_e32 v159, v159
	v_lshl_or_b32 v160, s65, 7, v156
	v_lshl_add_u32 v158, s66, 8, v140
	v_ashrrev_i32_e32 v161, 31, v160
	v_add_f32_e32 v159, 1.0, v159
	v_rcp_f32_e32 v159, v159
	v_mov_b64_e32 v[138:139], s[0:1]
	v_mad_i64_i32 v[162:163], s[28:29], v158, s91, v[138:139]
	v_mul_f32_e32 v124, v124, v159
	v_mul_f32_e32 v120, v124, v120
	v_mul_f32_e32 v124, 0xbfb8aa3b, v116
	v_exp_f32_e32 v124, v124
	s_mov_b64 s[50:51], -1
	s_andn2_b64 vcc, exec, s[36:37]
	v_add_f32_e32 v124, 1.0, v124
	v_rcp_f32_e32 v124, v124
	s_nop 0
	v_mul_f32_e32 v116, v116, v124
	v_mul_f32_e32 v116, v116, v112
	v_mul_f32_e32 v112, 0xbfb8aa3b, v125
	v_exp_f32_e32 v112, v112
	s_nop 0
	v_add_f32_e32 v112, 1.0, v112
	v_rcp_f32_e32 v112, v112
	s_nop 0
	v_mul_f32_e32 v112, v125, v112
	v_mul_f32_e32 v121, v112, v121
	v_mul_f32_e32 v112, 0xbfb8aa3b, v117
	v_exp_f32_e32 v112, v112
	s_nop 0
	v_add_f32_e32 v112, 1.0, v112
	v_rcp_f32_e32 v112, v112
	s_nop 0
	v_mul_f32_e32 v112, v117, v112
	v_mul_f32_e32 v117, v112, v113
	v_mul_f32_e32 v112, 0xbfb8aa3b, v126
	v_exp_f32_e32 v112, v112
	s_nop 0
	v_add_f32_e32 v112, 1.0, v112
	v_rcp_f32_e32 v112, v112
	s_nop 0
	v_mul_f32_e32 v112, v126, v112
	v_mul_f32_e32 v122, v112, v122
	v_mul_f32_e32 v112, 0xbfb8aa3b, v118
	v_exp_f32_e32 v112, v112
	s_nop 0
	v_add_f32_e32 v112, 1.0, v112
	v_rcp_f32_e32 v112, v112
	s_nop 0
	v_mul_f32_e32 v112, v118, v112
	v_mul_f32_e32 v124, v112, v114
	v_mul_f32_e32 v112, 0xbfb8aa3b, v127
	v_exp_f32_e32 v112, v112
	v_cvt_pk_bf16_f32 v114, v120, v121
	s_nop 0
	v_add_f32_e32 v112, 1.0, v112
	v_rcp_f32_e32 v112, v112
	s_nop 0
	v_mul_f32_e32 v112, v127, v112
	v_mul_f32_e32 v123, v112, v123
	v_mul_f32_e32 v112, 0xbfb8aa3b, v119
	v_exp_f32_e32 v112, v112
	s_nop 0
	v_add_f32_e32 v112, 1.0, v112
	v_rcp_f32_e32 v112, v112
	s_nop 0
	v_mul_f32_e32 v112, v119, v112
	v_mul_f32_e32 v125, v112, v115
	v_lshlrev_b64 v[112:113], 1, v[160:161]
	v_cvt_pk_bf16_f32 v115, v122, v123
	v_cvt_pk_bf16_f32 v116, v116, v117
	v_lshl_add_u64 v[118:119], v[162:163], 0, v[112:113]
	v_cvt_pk_bf16_f32 v117, v124, v125
	s_nop 0
	s_bitcmp1_b32 s66, 3
	s_cbranch_scc1 .Lact_keep0
	global_store_dwordx4 v[118:119], v[114:117], off sc1 nt
	s_branch .Lact_done0
.Lact_keep0:
	global_store_dwordx4 v[118:119], v[114:117], off sc1
.Lact_done0:
	s_nop 1
	v_mul_f32_e32 v116, 0xbfb8aa3b, v108
	v_exp_f32_e32 v116, v116
	v_or_b32_e32 v114, 16, v158
	v_mad_i64_i32 v[114:115], s[28:29], v114, s91, v[138:139]
	v_add_f32_e32 v116, 1.0, v116
	v_rcp_f32_e32 v116, v116
	s_nop 0
	v_mul_f32_e32 v108, v108, v116
	v_mul_f32_e32 v104, v108, v104
	v_mul_f32_e32 v108, 0xbfb8aa3b, v100
	v_exp_f32_e32 v108, v108
	s_nop 0
	v_add_f32_e32 v108, 1.0, v108
	v_rcp_f32_e32 v108, v108
	s_nop 0
	v_mul_f32_e32 v100, v100, v108
	v_mul_f32_e32 v108, v100, v96
	v_mul_f32_e32 v96, 0xbfb8aa3b, v109
	v_mul_f32_e32 v100, 0xbfb8aa3b, v101
	v_exp_f32_e32 v96, v96
	v_exp_f32_e32 v100, v100
	v_add_f32_e32 v96, 1.0, v96
	v_add_f32_e32 v100, 1.0, v100
	v_rcp_f32_e32 v96, v96
	v_rcp_f32_e32 v100, v100
	v_mul_f32_e32 v96, v109, v96
	v_mul_f32_e32 v100, v101, v100
	v_mul_f32_e32 v96, v96, v105
	v_mul_f32_e32 v105, v100, v97
	v_mul_f32_e32 v100, 0xbfb8aa3b, v102
	v_exp_f32_e32 v100, v100
	v_mul_f32_e32 v97, 0xbfb8aa3b, v110
	v_exp_f32_e32 v97, v97
	v_cvt_pk_bf16_f32 v96, v104, v96
	v_add_f32_e32 v100, 1.0, v100
	v_rcp_f32_e32 v100, v100
	v_add_f32_e32 v97, 1.0, v97
	v_rcp_f32_e32 v97, v97
	v_mul_f32_e32 v100, v102, v100
	v_mul_f32_e32 v102, v100, v98
	v_mul_f32_e32 v98, 0xbfb8aa3b, v111
	v_exp_f32_e32 v98, v98
	v_mul_f32_e32 v100, 0xbfb8aa3b, v103
	v_exp_f32_e32 v100, v100
	v_mul_f32_e32 v97, v110, v97
	v_add_f32_e32 v98, 1.0, v98
	v_rcp_f32_e32 v98, v98
	v_add_f32_e32 v100, 1.0, v100
	v_rcp_f32_e32 v100, v100
	v_mul_f32_e32 v97, v97, v106
	v_mul_f32_e32 v98, v111, v98
	v_mul_f32_e32 v98, v98, v107
	v_mul_f32_e32 v100, v103, v100
	v_mul_f32_e32 v99, v100, v99
	v_cvt_pk_bf16_f32 v97, v97, v98
	v_cvt_pk_bf16_f32 v98, v108, v105
	v_lshl_add_u64 v[100:101], v[114:115], 0, v[112:113]
	v_cvt_pk_bf16_f32 v99, v102, v99
	s_nop 0
	s_bitcmp1_b32 s66, 3
	s_cbranch_scc1 .Lact_keep1
	global_store_dwordx4 v[100:101], v[96:99], off sc1 nt
	s_branch .Lact_done1
.Lact_keep1:
	global_store_dwordx4 v[100:101], v[96:99], off sc1
.Lact_done1:
	s_nop 1
	v_mul_f32_e32 v98, 0xbfb8aa3b, v92
	v_exp_f32_e32 v98, v98
	v_or_b32_e32 v96, 32, v158
	v_mad_i64_i32 v[96:97], s[28:29], v96, s91, v[138:139]
	v_add_f32_e32 v98, 1.0, v98
	v_rcp_f32_e32 v98, v98
	s_nop 0
	v_mul_f32_e32 v92, v92, v98
	v_mul_f32_e32 v88, v92, v88
	v_mul_f32_e32 v92, 0xbfb8aa3b, v84
	v_exp_f32_e32 v92, v92
	s_nop 0
	v_add_f32_e32 v92, 1.0, v92
	v_rcp_f32_e32 v92, v92
	s_nop 0
	v_mul_f32_e32 v84, v84, v92
	v_mul_f32_e32 v92, v84, v80
	v_mul_f32_e32 v80, 0xbfb8aa3b, v93
	v_mul_f32_e32 v84, 0xbfb8aa3b, v85
	v_exp_f32_e32 v80, v80
	v_exp_f32_e32 v84, v84
	v_add_f32_e32 v80, 1.0, v80
	v_add_f32_e32 v84, 1.0, v84
	v_rcp_f32_e32 v80, v80
	v_rcp_f32_e32 v84, v84
	v_mul_f32_e32 v80, v93, v80
	v_mul_f32_e32 v84, v85, v84
	v_mul_f32_e32 v80, v80, v89
	v_mul_f32_e32 v89, v84, v81
	v_mul_f32_e32 v84, 0xbfb8aa3b, v86
	v_exp_f32_e32 v84, v84
	v_mul_f32_e32 v81, 0xbfb8aa3b, v94
	v_exp_f32_e32 v81, v81
	v_cvt_pk_bf16_f32 v80, v88, v80
	v_add_f32_e32 v84, 1.0, v84
	v_rcp_f32_e32 v84, v84
	v_add_f32_e32 v81, 1.0, v81
	v_rcp_f32_e32 v81, v81
	v_mul_f32_e32 v84, v86, v84
	v_mul_f32_e32 v86, v84, v82
	v_mul_f32_e32 v82, 0xbfb8aa3b, v95
	v_exp_f32_e32 v82, v82
	v_mul_f32_e32 v84, 0xbfb8aa3b, v87
	v_exp_f32_e32 v84, v84
	v_mul_f32_e32 v81, v94, v81
	v_add_f32_e32 v82, 1.0, v82
	v_rcp_f32_e32 v82, v82
	v_add_f32_e32 v84, 1.0, v84
	v_rcp_f32_e32 v84, v84
	v_mul_f32_e32 v81, v81, v90
	v_mul_f32_e32 v82, v95, v82
	v_mul_f32_e32 v82, v82, v91
	v_mul_f32_e32 v84, v87, v84
	v_mul_f32_e32 v83, v84, v83
	v_cvt_pk_bf16_f32 v81, v81, v82
	v_cvt_pk_bf16_f32 v82, v92, v89
	v_lshl_add_u64 v[84:85], v[96:97], 0, v[112:113]
	v_cvt_pk_bf16_f32 v83, v86, v83
	s_nop 0
	s_bitcmp1_b32 s66, 3
	s_cbranch_scc1 .Lact_keep2
	global_store_dwordx4 v[84:85], v[80:83], off sc1 nt
	s_branch .Lact_done2
.Lact_keep2:
	global_store_dwordx4 v[84:85], v[80:83], off sc1
.Lact_done2:
	s_nop 1
	v_mul_f32_e32 v82, 0xbfb8aa3b, v76
	v_exp_f32_e32 v82, v82
	v_or_b32_e32 v80, 48, v158
	v_mad_i64_i32 v[80:81], s[28:29], v80, s91, v[138:139]
	v_add_f32_e32 v82, 1.0, v82
	v_rcp_f32_e32 v82, v82
	s_nop 0
	v_mul_f32_e32 v76, v76, v82
	v_mul_f32_e32 v72, v76, v72
	v_mul_f32_e32 v76, 0xbfb8aa3b, v68
	v_exp_f32_e32 v76, v76
	s_nop 0
	v_add_f32_e32 v76, 1.0, v76
	v_rcp_f32_e32 v76, v76
	s_nop 0
	v_mul_f32_e32 v68, v68, v76
	v_mul_f32_e32 v76, v68, v64
	v_mul_f32_e32 v64, 0xbfb8aa3b, v77
	v_mul_f32_e32 v68, 0xbfb8aa3b, v69
	v_exp_f32_e32 v64, v64
	v_exp_f32_e32 v68, v68
	v_add_f32_e32 v64, 1.0, v64
	v_add_f32_e32 v68, 1.0, v68
	v_rcp_f32_e32 v64, v64
	v_rcp_f32_e32 v68, v68
	v_mul_f32_e32 v64, v77, v64
	v_mul_f32_e32 v68, v69, v68
	v_mul_f32_e32 v64, v64, v73
	v_mul_f32_e32 v73, v68, v65
	v_mul_f32_e32 v68, 0xbfb8aa3b, v70
	v_exp_f32_e32 v68, v68
	v_mul_f32_e32 v65, 0xbfb8aa3b, v78
	v_exp_f32_e32 v65, v65
	v_cvt_pk_bf16_f32 v64, v72, v64
	v_add_f32_e32 v68, 1.0, v68
	v_rcp_f32_e32 v68, v68
	v_add_f32_e32 v65, 1.0, v65
	v_rcp_f32_e32 v65, v65
	v_mul_f32_e32 v68, v70, v68
	v_mul_f32_e32 v70, v68, v66
	v_mul_f32_e32 v66, 0xbfb8aa3b, v79
	v_exp_f32_e32 v66, v66
	v_mul_f32_e32 v68, 0xbfb8aa3b, v71
	v_exp_f32_e32 v68, v68
	v_mul_f32_e32 v65, v78, v65
	v_add_f32_e32 v66, 1.0, v66
	v_rcp_f32_e32 v66, v66
	v_add_f32_e32 v68, 1.0, v68
	v_rcp_f32_e32 v68, v68
	v_mul_f32_e32 v65, v65, v74
	v_mul_f32_e32 v66, v79, v66
	v_mul_f32_e32 v66, v66, v75
	v_mul_f32_e32 v68, v71, v68
	v_mul_f32_e32 v67, v68, v67
	v_cvt_pk_bf16_f32 v65, v65, v66
	v_cvt_pk_bf16_f32 v66, v76, v73
	v_lshl_add_u64 v[68:69], v[80:81], 0, v[112:113]
	v_cvt_pk_bf16_f32 v67, v70, v67
	s_nop 0
	s_bitcmp1_b32 s66, 3
	s_cbranch_scc1 .Lact_keep3
	global_store_dwordx4 v[68:69], v[64:67], off sc1 nt
	s_branch .Lact_done3
.Lact_keep3:
	global_store_dwordx4 v[68:69], v[64:67], off sc1
.Lact_done3:
	s_nop 1
	v_mul_f32_e32 v66, 0xbfb8aa3b, v60
	v_exp_f32_e32 v66, v66
	v_add_u32_e32 v64, 0x80, v158
	v_mad_i64_i32 v[64:65], s[28:29], v64, s91, v[138:139]
	v_add_f32_e32 v66, 1.0, v66
	v_rcp_f32_e32 v66, v66
	s_nop 0
	v_mul_f32_e32 v60, v60, v66
	v_mul_f32_e32 v56, v60, v56
	v_mul_f32_e32 v60, 0xbfb8aa3b, v52
	v_exp_f32_e32 v60, v60
	s_nop 0
	v_add_f32_e32 v60, 1.0, v60
	v_rcp_f32_e32 v60, v60
	s_nop 0
	v_mul_f32_e32 v52, v52, v60
	v_mul_f32_e32 v60, v52, v48
	v_mul_f32_e32 v48, 0xbfb8aa3b, v61
	v_mul_f32_e32 v52, 0xbfb8aa3b, v53
	v_exp_f32_e32 v48, v48
	v_exp_f32_e32 v52, v52
	v_add_f32_e32 v48, 1.0, v48
	v_add_f32_e32 v52, 1.0, v52
	v_rcp_f32_e32 v48, v48
	v_rcp_f32_e32 v52, v52
	v_mul_f32_e32 v48, v61, v48
	v_mul_f32_e32 v52, v53, v52
	v_mul_f32_e32 v48, v48, v57
	v_mul_f32_e32 v57, v52, v49
	v_mul_f32_e32 v52, 0xbfb8aa3b, v54
	v_exp_f32_e32 v52, v52
	v_mul_f32_e32 v49, 0xbfb8aa3b, v62
	v_exp_f32_e32 v49, v49
	v_cvt_pk_bf16_f32 v48, v56, v48
	v_add_f32_e32 v52, 1.0, v52
	v_rcp_f32_e32 v52, v52
	v_add_f32_e32 v49, 1.0, v49
	v_rcp_f32_e32 v49, v49
	v_mul_f32_e32 v52, v54, v52
	v_mul_f32_e32 v54, v52, v50
	v_mul_f32_e32 v50, 0xbfb8aa3b, v63
	v_exp_f32_e32 v50, v50
	v_mul_f32_e32 v52, 0xbfb8aa3b, v55
	v_exp_f32_e32 v52, v52
	v_mul_f32_e32 v49, v62, v49
	v_add_f32_e32 v50, 1.0, v50
	v_rcp_f32_e32 v50, v50
	v_add_f32_e32 v52, 1.0, v52
	v_rcp_f32_e32 v52, v52
	v_mul_f32_e32 v49, v49, v58
	v_mul_f32_e32 v50, v63, v50
	v_mul_f32_e32 v50, v50, v59
	v_mul_f32_e32 v52, v55, v52
	v_mul_f32_e32 v51, v52, v51
	v_cvt_pk_bf16_f32 v49, v49, v50
	v_cvt_pk_bf16_f32 v50, v60, v57
	v_lshl_add_u64 v[52:53], v[64:65], 0, v[112:113]
	v_cvt_pk_bf16_f32 v51, v54, v51
	s_nop 0
	s_bitcmp1_b32 s66, 3
	s_cbranch_scc1 .Lact_keep4
	global_store_dwordx4 v[52:53], v[48:51], off sc1 nt
	s_branch .Lact_done4
.Lact_keep4:
	global_store_dwordx4 v[52:53], v[48:51], off sc1
.Lact_done4:
	s_nop 1
	v_mul_f32_e32 v50, 0xbfb8aa3b, v44
	v_exp_f32_e32 v50, v50
	v_add_u32_e32 v48, 0x90, v158
	v_mad_i64_i32 v[48:49], s[28:29], v48, s91, v[138:139]
	v_add_f32_e32 v50, 1.0, v50
	v_rcp_f32_e32 v50, v50
	s_nop 0
	v_mul_f32_e32 v44, v44, v50
	v_mul_f32_e32 v40, v44, v40
	v_mul_f32_e32 v44, 0xbfb8aa3b, v36
	v_exp_f32_e32 v44, v44
	s_nop 0
	v_add_f32_e32 v44, 1.0, v44
	v_rcp_f32_e32 v44, v44
	s_nop 0
	v_mul_f32_e32 v36, v36, v44
	v_mul_f32_e32 v44, v36, v32
	v_mul_f32_e32 v32, 0xbfb8aa3b, v45
	v_mul_f32_e32 v36, 0xbfb8aa3b, v37
	v_exp_f32_e32 v32, v32
	v_exp_f32_e32 v36, v36
	v_add_f32_e32 v32, 1.0, v32
	v_add_f32_e32 v36, 1.0, v36
	v_rcp_f32_e32 v32, v32
	v_rcp_f32_e32 v36, v36
	v_mul_f32_e32 v32, v45, v32
	v_mul_f32_e32 v36, v37, v36
	v_mul_f32_e32 v32, v32, v41
	v_mul_f32_e32 v41, v36, v33
	v_mul_f32_e32 v36, 0xbfb8aa3b, v38
	v_exp_f32_e32 v36, v36
	v_mul_f32_e32 v33, 0xbfb8aa3b, v46
	v_exp_f32_e32 v33, v33
	v_cvt_pk_bf16_f32 v32, v40, v32
	v_add_f32_e32 v36, 1.0, v36
	v_rcp_f32_e32 v36, v36
	v_add_f32_e32 v33, 1.0, v33
	v_rcp_f32_e32 v33, v33
	v_mul_f32_e32 v36, v38, v36
	v_mul_f32_e32 v38, v36, v34
	v_mul_f32_e32 v34, 0xbfb8aa3b, v47
	v_exp_f32_e32 v34, v34
	v_mul_f32_e32 v36, 0xbfb8aa3b, v39
	v_exp_f32_e32 v36, v36
	v_mul_f32_e32 v33, v46, v33
	v_add_f32_e32 v34, 1.0, v34
	v_rcp_f32_e32 v34, v34
	v_add_f32_e32 v36, 1.0, v36
	v_rcp_f32_e32 v36, v36
	v_mul_f32_e32 v33, v33, v42
	v_mul_f32_e32 v34, v47, v34
	v_mul_f32_e32 v34, v34, v43
	v_mul_f32_e32 v36, v39, v36
	v_mul_f32_e32 v35, v36, v35
	v_cvt_pk_bf16_f32 v33, v33, v34
	v_cvt_pk_bf16_f32 v34, v44, v41
	v_lshl_add_u64 v[36:37], v[48:49], 0, v[112:113]
	v_cvt_pk_bf16_f32 v35, v38, v35
	s_nop 0
	s_bitcmp1_b32 s66, 3
	s_cbranch_scc1 .Lact_keep5
	global_store_dwordx4 v[36:37], v[32:35], off sc1 nt
	s_branch .Lact_done5
.Lact_keep5:
	global_store_dwordx4 v[36:37], v[32:35], off sc1
.Lact_done5:
	s_nop 1
	v_mul_f32_e32 v34, 0xbfb8aa3b, v28
	v_exp_f32_e32 v34, v34
	v_add_u32_e32 v32, 0xa0, v158
	v_mad_i64_i32 v[32:33], s[28:29], v32, s91, v[138:139]
	v_add_f32_e32 v34, 1.0, v34
	v_rcp_f32_e32 v34, v34
	s_nop 0
	v_mul_f32_e32 v28, v28, v34
	v_mul_f32_e32 v24, v28, v24
	v_mul_f32_e32 v28, 0xbfb8aa3b, v20
	v_exp_f32_e32 v28, v28
	s_nop 0
	v_add_f32_e32 v28, 1.0, v28
	v_rcp_f32_e32 v28, v28
	s_nop 0
	v_mul_f32_e32 v20, v20, v28
	v_mul_f32_e32 v28, v20, v16
	v_mul_f32_e32 v16, 0xbfb8aa3b, v29
	v_mul_f32_e32 v20, 0xbfb8aa3b, v21
	v_exp_f32_e32 v16, v16
	v_exp_f32_e32 v20, v20
	v_add_f32_e32 v16, 1.0, v16
	v_add_f32_e32 v20, 1.0, v20
	v_rcp_f32_e32 v16, v16
	v_rcp_f32_e32 v20, v20
	v_mul_f32_e32 v16, v29, v16
	v_mul_f32_e32 v20, v21, v20
	v_mul_f32_e32 v16, v16, v25
	v_mul_f32_e32 v25, v20, v17
	v_mul_f32_e32 v20, 0xbfb8aa3b, v22
	v_exp_f32_e32 v20, v20
	v_mul_f32_e32 v17, 0xbfb8aa3b, v30
	v_exp_f32_e32 v17, v17
	v_cvt_pk_bf16_f32 v16, v24, v16
	v_add_f32_e32 v20, 1.0, v20
	v_rcp_f32_e32 v20, v20
	v_add_f32_e32 v17, 1.0, v17
	v_rcp_f32_e32 v17, v17
	v_mul_f32_e32 v20, v22, v20
	v_mul_f32_e32 v22, v20, v18
	v_mul_f32_e32 v18, 0xbfb8aa3b, v31
	v_exp_f32_e32 v18, v18
	v_mul_f32_e32 v20, 0xbfb8aa3b, v23
	v_exp_f32_e32 v20, v20
	v_mul_f32_e32 v17, v30, v17
	v_add_f32_e32 v18, 1.0, v18
	v_rcp_f32_e32 v18, v18
	v_add_f32_e32 v20, 1.0, v20
	v_rcp_f32_e32 v20, v20
	v_mul_f32_e32 v17, v17, v26
	v_mul_f32_e32 v18, v31, v18
	v_mul_f32_e32 v18, v18, v27
	v_mul_f32_e32 v20, v23, v20
	v_mul_f32_e32 v19, v20, v19
	v_cvt_pk_bf16_f32 v17, v17, v18
	v_cvt_pk_bf16_f32 v18, v28, v25
	v_lshl_add_u64 v[20:21], v[32:33], 0, v[112:113]
	v_cvt_pk_bf16_f32 v19, v22, v19
	s_nop 0
	s_bitcmp1_b32 s66, 3
	s_cbranch_scc1 .Lact_keep6
	global_store_dwordx4 v[20:21], v[16:19], off sc1 nt
	s_branch .Lact_done6
.Lact_keep6:
	global_store_dwordx4 v[20:21], v[16:19], off sc1
.Lact_done6:
	s_nop 1
	v_mul_f32_e32 v18, 0xbfb8aa3b, v12
	v_exp_f32_e32 v18, v18
	v_add_u32_e32 v16, 0xb0, v158
	v_mad_i64_i32 v[16:17], s[28:29], v16, s91, v[138:139]
	v_add_f32_e32 v18, 1.0, v18
	v_rcp_f32_e32 v18, v18
	s_nop 0
	v_mul_f32_e32 v12, v12, v18
	v_mul_f32_e32 v8, v12, v8
	v_mul_f32_e32 v12, 0xbfb8aa3b, v4
	v_exp_f32_e32 v12, v12
	s_nop 0
	v_add_f32_e32 v12, 1.0, v12
	v_rcp_f32_e32 v12, v12
	s_nop 0
	v_mul_f32_e32 v4, v4, v12
	v_mul_f32_e32 v12, v4, v0
	v_mul_f32_e32 v0, 0xbfb8aa3b, v13
	v_mul_f32_e32 v4, 0xbfb8aa3b, v5
	v_exp_f32_e32 v0, v0
	v_exp_f32_e32 v4, v4
	v_add_f32_e32 v0, 1.0, v0
	v_add_f32_e32 v4, 1.0, v4
	v_rcp_f32_e32 v0, v0
	v_rcp_f32_e32 v4, v4
	v_mul_f32_e32 v0, v13, v0
	v_mul_f32_e32 v4, v5, v4
	v_mul_f32_e32 v0, v0, v9
	v_mul_f32_e32 v9, v4, v1
	v_mul_f32_e32 v4, 0xbfb8aa3b, v6
	v_exp_f32_e32 v4, v4
	v_mul_f32_e32 v1, 0xbfb8aa3b, v14
	v_exp_f32_e32 v1, v1
	v_cvt_pk_bf16_f32 v0, v8, v0
	v_add_f32_e32 v4, 1.0, v4
	v_rcp_f32_e32 v4, v4
	v_add_f32_e32 v1, 1.0, v1
	v_rcp_f32_e32 v1, v1
	v_mul_f32_e32 v4, v6, v4
	v_mul_f32_e32 v6, v4, v2
	v_mul_f32_e32 v2, 0xbfb8aa3b, v15
	v_mul_f32_e32 v4, 0xbfb8aa3b, v7
	v_exp_f32_e32 v2, v2
	v_exp_f32_e32 v4, v4
	v_mul_f32_e32 v1, v14, v1
	v_mul_f32_e32 v1, v1, v10
	v_add_f32_e32 v2, 1.0, v2
	v_add_f32_e32 v4, 1.0, v4
	v_rcp_f32_e32 v2, v2
	v_rcp_f32_e32 v4, v4
	v_mul_f32_e32 v2, v15, v2
	v_mul_f32_e32 v4, v7, v4
	v_mul_f32_e32 v2, v2, v11
	v_mul_f32_e32 v3, v4, v3
	v_lshl_add_u64 v[4:5], v[16:17], 0, v[112:113]
	v_cvt_pk_bf16_f32 v1, v1, v2
	v_cvt_pk_bf16_f32 v2, v12, v9
	v_cvt_pk_bf16_f32 v3, v6, v3
	s_nop 0
	s_bitcmp1_b32 s66, 3
	s_cbranch_scc1 .Lact_keep7
	global_store_dwordx4 v[4:5], v[0:3], off sc1 nt
	s_branch .Lact_done7
.Lact_keep7:
	global_store_dwordx4 v[4:5], v[0:3], off sc1
.Lact_done7:
	s_nop 1
	s_cbranch_vccnz .LBB0_176
	s_andn2_b64 vcc, exec, s[38:39]
	s_cbranch_vccnz .LBB0_175
	s_barrier
	s_branch .LBB0_175
